# attention row-max reduction as two independent interleaved v_max3 chains instead of one serial chain (8 sites, exact)
# baseline (speedup 1.0000x reference)
.Lj3ld_norka:
	s_or_b64 exec, exec, s[6:7]
	s_waitcnt lgkmcnt(0)
	v_mfma_f32_32x32x16_bf16 v[130:145], v[232:235], v[236:239], v[130:145]
	s_nop 11
	v_mov_b32_e32 v146, v130
	v_mov_b32_e32 v147, v131
	v_max3_f32 v130, v146, v147, v132
	v_max3_f32 v131, v139, v140, v141
	v_max3_f32 v130, v130, v133, v134
	v_max3_f32 v131, v131, v142, v143
	v_max3_f32 v130, v130, v135, v136
	v_max3_f32 v131, v131, v144, v145
	v_max3_f32 v130, v130, v137, v138
	v_max_f32_e32 v130, v130, v131
	v_sub_f32_e32 v131, v230, v130
	v_cmp_gt_f32_e32 vcc, 0xc2200000, v131
	s_cbranch_vccnz .Llazy0_full
	ds_read_b64_tr_b16 v[232:233], v222
	ds_read_b64_tr_b16 v[234:235], v222 offset:4736
	ds_read_b64_tr_b16 v[236:237], v222 offset:64
	ds_read_b64_tr_b16 v[238:239], v222 offset:4800
	ds_read_b64_tr_b16 v[240:241], v222 offset:128
	ds_read_b64_tr_b16 v[242:243], v222 offset:4864
	ds_read_b64_tr_b16 v[246:247], v222 offset:192
	ds_read_b64_tr_b16 v[248:249], v222 offset:4928
	v_mov_b32_e32 v229, v230
	v_mov_b32_e32 v130, 1.0
	s_branch .LBB0_946

.LBB0_1005:
	s_nop 0
	v_max3_f32 v64, v171, v169, v52
	v_max3_f32 v65, v160, v59, v161
	v_max3_f32 v64, v64, v166, v53
	v_max3_f32 v65, v65, v60, v158
	v_max3_f32 v64, v64, v167, v168
	v_max3_f32 v65, v65, v61, v159
	v_max3_f32 v64, v64, v170, v54
	v_max3_f32 v65, v65, v62, v156
	v_max3_f32 v64, v64, v164, v55
	v_max3_f32 v65, v65, v63, v157
	v_max3_f32 v64, v64, v165, v56
	v_max3_f32 v65, v65, v50, v154
	v_max3_f32 v64, v64, v162, v57
	v_max3_f32 v65, v65, v51, v155
	v_max3_f32 v64, v64, v163, v58
	v_max_f32_e32 v64, v64, v65
	v_sub_f32_e32 v65, v181, v64
	v_cmp_gt_f32_e32 vcc, 0xc2200000, v65
	s_cbranch_vccnz .Llazy3_full
	s_waitcnt lgkmcnt(0)
	v_mov_b32_e32 v182, v181
	v_mov_b32_e32 v64, 1.0
	s_branch .LBB0_1007

.LBB0_1051:
	s_waitcnt lgkmcnt(0)
	s_nop 3
	s_nop 0
	v_max3_f32 v178, v99, v115, v100
	v_max3_f32 v179, v122, v107, v123
	v_max3_f32 v178, v178, v116, v101
	v_max3_f32 v179, v179, v108, v124
	v_max3_f32 v178, v178, v117, v114
	v_max3_f32 v179, v179, v109, v125
	v_max3_f32 v178, v178, v98, v102
	v_max3_f32 v179, v179, v110, v126
	v_max3_f32 v178, v178, v118, v103
	v_max3_f32 v179, v179, v111, v127
	v_max3_f32 v178, v178, v119, v104
	v_max3_f32 v179, v179, v112, v128
	v_max3_f32 v178, v178, v120, v105
	v_max3_f32 v179, v179, v113, v129
	v_max3_f32 v178, v178, v121, v106
	v_max_f32_e32 v178, v178, v179
	v_sub_f32_e32 v179, v205, v178
	v_cmp_gt_f32_e32 vcc, 0xc2200000, v179
	s_cbranch_vccnz .Llazy4_full
	s_waitcnt lgkmcnt(0)
	v_mov_b32_e32 v207, v205
	v_mov_b32_e32 v178, 1.0
	s_branch .LBB0_1053

.LBB0_1067:
	s_nop 3
	s_nop 0
	v_max3_f32 v114, v83, v67, v84
	v_max3_f32 v115, v74, v91, v75
	v_max3_f32 v114, v114, v68, v85
	v_max3_f32 v115, v115, v92, v76
	v_max3_f32 v114, v114, v69, v66
	v_max3_f32 v115, v115, v93, v77
	v_max3_f32 v114, v114, v82, v86
	v_max3_f32 v115, v115, v94, v78
	v_max3_f32 v114, v114, v70, v87
	v_max3_f32 v115, v115, v95, v79
	v_max3_f32 v114, v114, v71, v88
	v_max3_f32 v115, v115, v96, v80
	v_max3_f32 v114, v114, v72, v89
	v_max3_f32 v115, v115, v97, v81
	v_max3_f32 v114, v114, v73, v90
	v_max_f32_e32 v114, v114, v115
	v_sub_f32_e32 v115, v204, v114
	v_cmp_gt_f32_e32 vcc, 0xc2200000, v115
	s_cbranch_vccnz .Llazy5_full
	s_waitcnt lgkmcnt(0)
	v_mov_b32_e32 v206, v204
	v_mov_b32_e32 v114, 1.0
	s_branch .LBB0_1069

.LBB0_1107:
	s_waitcnt lgkmcnt(0)
	s_nop 3
	s_nop 0
	v_max3_f32 v178, v99, v115, v100
	v_max3_f32 v179, v122, v107, v123
	v_max3_f32 v178, v178, v116, v101
	v_max3_f32 v179, v179, v108, v124
	v_max3_f32 v178, v178, v117, v114
	v_max3_f32 v179, v179, v109, v125
	v_max3_f32 v178, v178, v98, v102
	v_max3_f32 v179, v179, v110, v126
	v_max3_f32 v178, v178, v118, v103
	v_max3_f32 v179, v179, v111, v127
	v_max3_f32 v178, v178, v119, v104
	v_max3_f32 v179, v179, v112, v128
	v_max3_f32 v178, v178, v120, v105
	v_max3_f32 v179, v179, v113, v129
	v_max3_f32 v178, v178, v121, v106
	v_max_f32_e32 v178, v178, v179
	v_sub_f32_e32 v179, v207, v178
	v_cmp_gt_f32_e32 vcc, 0xc2200000, v179
	s_cbranch_vccnz .Llazy6_full
	s_waitcnt lgkmcnt(0)
	v_mov_b32_e32 v205, v207
	v_mov_b32_e32 v178, 1.0
	s_branch .LBB0_1109

.LBB0_1124:
	s_nop 3
	s_nop 0
	v_max3_f32 v114, v83, v67, v84
	v_max3_f32 v115, v74, v91, v75
	v_max3_f32 v114, v114, v68, v85
	v_max3_f32 v115, v115, v92, v76
	v_max3_f32 v114, v114, v69, v66
	v_max3_f32 v115, v115, v93, v77
	v_max3_f32 v114, v114, v82, v86
	v_max3_f32 v115, v115, v94, v78
	v_max3_f32 v114, v114, v70, v87
	v_max3_f32 v115, v115, v95, v79
	v_max3_f32 v114, v114, v71, v88
	v_max3_f32 v115, v115, v96, v80
	v_max3_f32 v114, v114, v72, v89
	v_max3_f32 v115, v115, v97, v81
	v_max3_f32 v114, v114, v73, v90
	v_max_f32_e32 v114, v114, v115
	v_sub_f32_e32 v115, v206, v114
	v_cmp_gt_f32_e32 vcc, 0xc2200000, v115
	s_cbranch_vccnz .Llazy7_full
	s_waitcnt lgkmcnt(0)
	v_mov_b32_e32 v204, v206
	v_mov_b32_e32 v114, 1.0
	s_branch .LBB0_1126

.LBB0_1165:
	s_sub_i32 s45, s42, 64
	s_cmp_ge_u32 s45, s66
	s_cselect_b64 s[48:49], -1, 0
	s_cmp_gt_i32 s44, s39
	s_cselect_b64 s[50:51], -1, 0
	s_or_b64 s[48:49], s[50:51], s[48:49]
	s_and_b64 vcc, exec, s[48:49]
	s_cbranch_vccnz .LBB0_1169
	v_add_u32_e32 v120, v124, v198
	ds_read_b128 v[136:139], v120
	ds_read_b128 v[140:143], v120 offset:6656
	ds_read_b128 v[144:147], v120 offset:32
	ds_read_b128 v[148:151], v120 offset:6688
	ds_read_b128 v[152:155], v120 offset:64
	ds_read_b128 v[156:159], v120 offset:6720
	ds_read_b128 v[160:163], v120 offset:96
	ds_read_b128 v[164:167], v120 offset:6752
	ds_read_b128 v[168:171], v120 offset:128
	ds_read_b128 v[172:175], v120 offset:6784
	ds_read_b128 v[176:179], v120 offset:160
	ds_read_b128 v[180:183], v120 offset:6816
	v_add_u32_e32 v184, v125, v126
	s_waitcnt lgkmcnt(11)
	v_mfma_f32_32x32x16_bf16 v[34:49], v[136:139], v[66:69], v[220:235]
	s_waitcnt lgkmcnt(10)
	v_mfma_f32_32x32x16_bf16 v[50:65], v[140:143], v[66:69], v[220:235]
	s_waitcnt lgkmcnt(9)
	v_mfma_f32_32x32x16_bf16 v[34:49], v[144:147], v[70:73], v[34:49]
	s_waitcnt lgkmcnt(8)
	v_mfma_f32_32x32x16_bf16 v[50:65], v[148:151], v[70:73], v[50:65]
	s_waitcnt lgkmcnt(7)
	v_mfma_f32_32x32x16_bf16 v[34:49], v[152:155], v[74:77], v[34:49]
	s_waitcnt lgkmcnt(6)
	v_mfma_f32_32x32x16_bf16 v[50:65], v[156:159], v[74:77], v[50:65]
	s_waitcnt lgkmcnt(5)
	v_mfma_f32_32x32x16_bf16 v[34:49], v[160:163], v[78:81], v[34:49]
	s_waitcnt lgkmcnt(4)
	v_mfma_f32_32x32x16_bf16 v[50:65], v[164:167], v[78:81], v[50:65]
	s_waitcnt lgkmcnt(3)
	v_mfma_f32_32x32x16_bf16 v[34:49], v[168:171], v[106:109], v[34:49]
	s_waitcnt lgkmcnt(2)
	v_mfma_f32_32x32x16_bf16 v[50:65], v[172:175], v[106:109], v[50:65]
	s_waitcnt lgkmcnt(1)
	v_mfma_f32_32x32x16_bf16 v[34:49], v[176:179], v[110:113], v[34:49]
	s_waitcnt lgkmcnt(0)
	v_mfma_f32_32x32x16_bf16 v[50:65], v[180:183], v[110:113], v[50:65]
	s_nop 11
	v_max3_f32 v120, v34, v35, v36
	v_max3_f32 v130, v51, v52, v53
	v_max3_f32 v120, v120, v37, v38
	v_max3_f32 v130, v130, v54, v55
	v_max3_f32 v120, v120, v39, v40
	v_max3_f32 v130, v130, v56, v57
	v_max3_f32 v120, v120, v41, v42
	v_max3_f32 v130, v130, v58, v59
	v_max3_f32 v120, v120, v43, v44
	v_max3_f32 v130, v130, v60, v61
	v_max3_f32 v120, v120, v45, v46
	v_max3_f32 v130, v130, v62, v63
	v_max3_f32 v120, v120, v47, v48
	v_max3_f32 v130, v130, v64, v65
	v_max3_f32 v120, v120, v49, v50
	v_max_f32_e32 v120, v120, v130
	v_sub_f32_e32 v130, v236, v120
	v_cmp_gt_f32_e32 vcc, 0xc2200000, v130
	s_cbranch_vccnz .Llazy8_full
	ds_read_b64_tr_b16 v[136:137], v184 offset:13312
	ds_read_b64_tr_b16 v[138:139], v184 offset:14464
	ds_read_b64_tr_b16 v[140:141], v184 offset:13376
	ds_read_b64_tr_b16 v[142:143], v184 offset:14528
	ds_read_b64_tr_b16 v[144:145], v184 offset:15616
	ds_read_b64_tr_b16 v[146:147], v184 offset:16768
	ds_read_b64_tr_b16 v[148:149], v184 offset:15680
	ds_read_b64_tr_b16 v[150:151], v184 offset:16832
	ds_read_b64_tr_b16 v[152:153], v184 offset:17920
	ds_read_b64_tr_b16 v[154:155], v184 offset:19072
	ds_read_b64_tr_b16 v[156:157], v184 offset:17984
	ds_read_b64_tr_b16 v[158:159], v184 offset:19136
	ds_read_b64_tr_b16 v[160:161], v184 offset:20224
	ds_read_b64_tr_b16 v[162:163], v184 offset:21376
	ds_read_b64_tr_b16 v[164:165], v184 offset:20288
	ds_read_b64_tr_b16 v[166:167], v184 offset:21440
	v_mov_b32_e32 v130, v129
	v_mov_b32_e32 v120, 1.0
	s_branch .LBB0_1168

.LBB0_1179:
	s_cmp_ge_u32 s42, s66
	s_cselect_b64 s[48:49], -1, 0
	s_cmp_ge_i32 s44, s39
	s_cselect_b64 s[50:51], -1, 0
	s_or_b64 s[48:49], s[50:51], s[48:49]
	s_and_b64 vcc, exec, s[48:49]
	s_cbranch_vccnz .LBB0_1184
	v_add_u32_e32 v120, v124, v198
	ds_read_b128 v[136:139], v120 offset:32768
	ds_read_b128 v[140:143], v120 offset:39424
	ds_read_b128 v[144:147], v120 offset:32800
	ds_read_b128 v[148:151], v120 offset:39456
	ds_read_b128 v[152:155], v120 offset:32832
	ds_read_b128 v[156:159], v120 offset:39488
	ds_read_b128 v[160:163], v120 offset:32864
	ds_read_b128 v[164:167], v120 offset:39520
	ds_read_b128 v[168:171], v120 offset:32896
	ds_read_b128 v[172:175], v120 offset:39552
	ds_read_b128 v[176:179], v120 offset:32928
	ds_read_b128 v[180:183], v120 offset:39584
	v_add_u32_e32 v184, v125, v126
	s_waitcnt lgkmcnt(11)
	v_mfma_f32_32x32x16_bf16 v[34:49], v[136:139], v[66:69], v[220:235]
	s_waitcnt lgkmcnt(10)
	v_mfma_f32_32x32x16_bf16 v[50:65], v[140:143], v[66:69], v[220:235]
	s_waitcnt lgkmcnt(9)
	v_mfma_f32_32x32x16_bf16 v[34:49], v[144:147], v[70:73], v[34:49]
	s_waitcnt lgkmcnt(8)
	v_mfma_f32_32x32x16_bf16 v[50:65], v[148:151], v[70:73], v[50:65]
	s_waitcnt lgkmcnt(7)
	v_mfma_f32_32x32x16_bf16 v[34:49], v[152:155], v[74:77], v[34:49]
	s_waitcnt lgkmcnt(6)
	v_mfma_f32_32x32x16_bf16 v[50:65], v[156:159], v[74:77], v[50:65]
	s_waitcnt lgkmcnt(5)
	v_mfma_f32_32x32x16_bf16 v[34:49], v[160:163], v[78:81], v[34:49]
	s_waitcnt lgkmcnt(4)
	v_mfma_f32_32x32x16_bf16 v[50:65], v[164:167], v[78:81], v[50:65]
	s_waitcnt lgkmcnt(3)
	v_mfma_f32_32x32x16_bf16 v[34:49], v[168:171], v[106:109], v[34:49]
	s_waitcnt lgkmcnt(2)
	v_mfma_f32_32x32x16_bf16 v[50:65], v[172:175], v[106:109], v[50:65]
	s_waitcnt lgkmcnt(1)
	v_mfma_f32_32x32x16_bf16 v[34:49], v[176:179], v[110:113], v[34:49]
	s_waitcnt lgkmcnt(0)
	v_mfma_f32_32x32x16_bf16 v[50:65], v[180:183], v[110:113], v[50:65]
	s_nop 11
	v_max3_f32 v120, v34, v35, v36
	v_max3_f32 v129, v51, v52, v53
	v_max3_f32 v120, v120, v37, v38
	v_max3_f32 v129, v129, v54, v55
	v_max3_f32 v120, v120, v39, v40
	v_max3_f32 v129, v129, v56, v57
	v_max3_f32 v120, v120, v41, v42
	v_max3_f32 v129, v129, v58, v59
	v_max3_f32 v120, v120, v43, v44
	v_max3_f32 v129, v129, v60, v61
	v_max3_f32 v120, v120, v45, v46
	v_max3_f32 v129, v129, v62, v63
	v_max3_f32 v120, v120, v47, v48
	v_max3_f32 v129, v129, v64, v65
	v_max3_f32 v120, v120, v49, v50
	v_max_f32_e32 v120, v120, v129
	v_sub_f32_e32 v129, v236, v120
	v_cmp_gt_f32_e32 vcc, 0xc2200000, v129
	s_cbranch_vccnz .Llazy9_full
	ds_read_b64_tr_b16 v[136:137], v184 offset:46080
	ds_read_b64_tr_b16 v[138:139], v184 offset:47232
	ds_read_b64_tr_b16 v[140:141], v184 offset:46144
	ds_read_b64_tr_b16 v[142:143], v184 offset:47296
	ds_read_b64_tr_b16 v[144:145], v184 offset:48384
	ds_read_b64_tr_b16 v[146:147], v184 offset:49536
	ds_read_b64_tr_b16 v[148:149], v184 offset:48448
	ds_read_b64_tr_b16 v[150:151], v184 offset:49600
	ds_read_b64_tr_b16 v[152:153], v184 offset:50688
	ds_read_b64_tr_b16 v[154:155], v184 offset:51840
	ds_read_b64_tr_b16 v[156:157], v184 offset:50752
	ds_read_b64_tr_b16 v[158:159], v184 offset:51904
	ds_read_b64_tr_b16 v[160:161], v184 offset:52992
	ds_read_b64_tr_b16 v[162:163], v184 offset:54144
	ds_read_b64_tr_b16 v[164:165], v184 offset:53056
	ds_read_b64_tr_b16 v[166:167], v184 offset:54208
	v_mov_b32_e32 v129, v130
	v_mov_b32_e32 v120, 1.0
	s_branch .LBB0_1182
